# static priority: one s_setprio 1 for the staggered (second-arriving) wave half at each GEMM phase entry, no per-segment toggling (on top of v55)
# speedup vs baseline: 1.0088x; 1.0062x over previous
; #define PG8_STAGE(bufoff, gbase, voff) do { _Pragma("unroll") for (int _i = 0; _i < 2; ++_i) \
;         __builtin_amdgcn_global_load_lds((const unsigned*)((const char*)(gbase) + (voff)[_i]), (PG8_LAS unsigned*)(lds + (bufoff) + ldsw + _i * 8192), 16, 0, 0); } while (0)
; #define PG8_BAR __builtin_amdgcn_s_barrier()
; template <class Epi, class Sched, bool ALIGN_EPI = false, bool SP2 = false>
; __device__ __forceinline__ void gemm_phase(PG8_LAS unsigned char* lds, const Gemm g, const Sched& S, const Epi& E) {
;     ...
;     for (int i = 0; i < 2; ++i) { int R, C; stage_rc(tid * 16 + i * 8192, R, C); const int Rb = Epi::PERM ? ((R & ~31) + perm32(R & 31)) : R;
;         voffA[i] = (unsigned)(R * g.lda + C) * 2u; voffB[i] = (unsigned)(Rb * g.ldb + C) * 2u; }
;     ...
;     const char* cA = PG8_ABASE(cur); const char* cB = (const char*)g.Bt + (size_t)cur.pn * tstepB;
;     S.a_ready(cur);
;     if constexpr (SP2) {
;         PG8_STAGE(PG8_SB(0, 0), cB, voffB); PG8_STAGE(PG8_SB(0, 1), cB + hstepB, voffB); PG8_STAGE(PG8_SA(0, 0), cA, voffA); PG8_STAGE(PG8_SA(0, 1), cA + hstepA, voffA);
;         if (wr == 1) PG8_BAR;
.LBB0_135:
	v_lshrrev_b32_e32 v4, 1, v0
	v_and_b32_e32 v14, 24, v4
	v_lshrrev_b32_e32 v4, 5, v0
	v_lshlrev_b32_e32 v2, 4, v0
	v_and_b32_e32 v3, 32, v0
	v_and_b32_e32 v4, 4, v4
	v_bfe_u32 v5, v0, 2, 2
	v_bfe_u32 v12, v0, 2, 4
	v_bitop3_b32 v10, v2, v3, 48 bitop3:0x6c
	v_and_b32_e32 v11, 64, v0
	v_or3_b32 v4, v4, v5, v14
	v_lshrrev_b32_e32 v5, 3, v0
	v_or_b32_e32 v13, 0x2000, v2
	v_or_b32_e32 v3, v10, v11
	v_and_or_b32 v6, v5, 48, v12
	v_and_or_b32 v5, v5, 32, v4
	v_lshrrev_b32_e32 v2, 7, v13
	s_movk_i32 s1, 0x70
	v_lshl_or_b32 v140, v5, 13, v3
	v_and_or_b32 v5, v2, s1, v12
	s_movk_i32 s1, 0x60
	v_and_or_b32 v2, v2, s1, v4
	s_lshr_b32 s5, s14, 6
	s_ashr_i32 s1, s0, 31
	s_ashr_i32 s55, s54, 31
	s_lshr_b32 s4, s14, 8
	s_lshl_b32 s66, s5, 10
	s_lshl_b64 s[6:7], s[0:1], 21
	s_lshl_b64 s[8:9], s[54:55], 21
	s_add_u32 s8, s12, s8
	s_addc_u32 s9, s13, s9
	s_add_i32 s55, s66, 0
	s_add_i32 m0, s55, 0x10000
	v_lshl_or_b32 v144, v2, 13, v3
	global_load_lds_dwordx4 v140, s[8:9]
	s_add_i32 m0, s55, 0x12000
	s_add_u32 s16, s8, 0x100000
	global_load_lds_dwordx4 v144, s[8:9]
	s_addc_u32 s17, s9, 0
	s_add_i32 m0, s55, 0x14000
	v_lshl_or_b32 v138, v6, 13, v3
	global_load_lds_dwordx4 v140, s[16:17]
	s_add_i32 m0, s55, 0x16000
	s_add_u32 s6, s38, s6
	s_addc_u32 s7, s39, s7
	s_add_i32 s67, s55, 0x2000
	global_load_lds_dwordx4 v144, s[16:17]
	s_mov_b32 m0, s55
	s_add_u32 s16, s6, 0x100000
	v_lshl_or_b32 v142, v5, 13, v3
	global_load_lds_dwordx4 v138, s[6:7]
	s_mov_b32 m0, s67
	s_addc_u32 s17, s7, 0
	s_add_i32 s72, s55, 0x4000
	global_load_lds_dwordx4 v142, s[6:7]
	s_mov_b32 m0, s72
	s_add_i32 s73, s55, 0x6000
	global_load_lds_dwordx4 v138, s[16:17]
	s_mov_b32 m0, s73
	v_mov_b32_e32 v147, 0
	global_load_lds_dwordx4 v142, s[16:17]
	v_mov_b32_e32 v141, v147
	v_mov_b32_e32 v145, v147
	v_mov_b32_e32 v139, v147
	v_mov_b32_e32 v143, v147
	s_cmp_eq_u32 s4, 1
	s_mov_b32 s84, s89
	s_mov_b64 s[78:79], s[90:91]
	s_mov_b32 s15, 0
	v_lshl_add_u64 v[8:9], s[8:9], 0, v[140:141]
	v_lshl_add_u64 v[4:5], s[8:9], 0, v[144:145]
	v_lshl_add_u64 v[2:3], s[6:7], 0, v[138:139]
	s_cselect_b64 s[16:17], -1, 0
	s_cmp_lg_u32 s4, 1
	v_lshl_add_u64 v[6:7], s[6:7], 0, v[142:143]
	s_cbranch_scc1 .LBB0_137
	s_barrier
	s_setprio 1

; #define PG8_STAGE(bufoff, gbase, voff) do { _Pragma("unroll") for (int _i = 0; _i < 2; ++_i) \
;         __builtin_amdgcn_global_load_lds((const unsigned*)((const char*)(gbase) + (voff)[_i]), (PG8_LAS unsigned*)(lds + (bufoff) + ldsw + _i * 8192), 16, 0, 0); } while (0)
; #define PG8_BAR __builtin_amdgcn_s_barrier()
;     __host__ __device__ bool next(int i, Unit& u) const {
;         const long L = (long)i * G + c; if (L >= nwg) return false;
;         int wgid = (int)L; { const int q = nwg / NXCD, r = nwg % NXCD, xcd = wgid % NXCD, off = wgid / NXCD; wgid = (xcd < r ? xcd * (q + 1) : r * (q + 1) + (xcd - r) * q) + off; }
;         const int nig = WGM * nN, gid = wgid / nig, fm = gid * WGM, gsz = (nM - fm) < WGM ? (nM - fm) : WGM;
;         u.pm = fm + ((wgid % nig) % gsz); u.pn = (wgid % nig) / gsz; return true;
; template <class Epi, class Sched, bool ALIGN_EPI = false, bool SP2 = false>
; __device__ __forceinline__ void gemm_phase(PG8_LAS unsigned char* lds, const Gemm g, const Sched& S, const Epi& E) {
;     ...
;     const char* cA = PG8_ABASE(cur); const char* cB = (const char*)g.Bt + (size_t)cur.pn * tstepB;
;     S.a_ready(cur);
;     if constexpr (SP2) {
;         PG8_STAGE(PG8_SB(0, 0), cB, voffB); PG8_STAGE(PG8_SB(0, 1), cB + hstepB, voffB); PG8_STAGE(PG8_SA(0, 0), cA, voffA); PG8_STAGE(PG8_SA(0, 1), cA + hstepA, voffA);
;         if (wr == 1) PG8_BAR;
.LBB0_464:
	v_lshrrev_b32_e32 v4, 1, v0
	v_and_b32_e32 v13, 24, v4
	v_lshrrev_b32_e32 v4, 5, v0
	v_lshlrev_b32_e32 v2, 4, v0
	v_and_b32_e32 v3, 32, v0
	v_and_b32_e32 v4, 4, v4
	v_bfe_u32 v5, v0, 2, 2
	v_bfe_u32 v12, v0, 2, 4
	v_bitop3_b32 v10, v2, v3, 48 bitop3:0x6c
	v_and_b32_e32 v11, 64, v0
	v_or3_b32 v4, v4, v5, v13
	v_lshrrev_b32_e32 v5, 3, v0
	v_or_b32_e32 v14, 0x2000, v2
	s_ashr_i32 s0, s5, 3
	v_or_b32_e32 v3, v10, v11
	v_and_or_b32 v6, v5, 48, v12
	v_and_or_b32 v5, v5, 32, v4
	v_lshrrev_b32_e32 v2, 7, v14
	s_movk_i32 s1, 0x70
	v_lshl_or_b32 v148, v5, 10, v3
	v_and_or_b32 v5, v2, s1, v12
	s_movk_i32 s1, 0x60
	s_add_i32 s0, s7, s0
	v_and_or_b32 v2, v2, s1, v4
	s_ashr_i32 s1, s0, 31
	s_lshr_b32 s1, s1, 26
	s_add_i32 s1, s0, s1
	s_ashr_i32 s7, s1, 6
	s_andn2_b32 s1, s1, 63
	s_sub_i32 s1, s0, s1
	s_bfe_i32 s0, s1, 0x80000
	s_bfe_u32 s0, s0, 0x3000c
	s_add_i32 s18, s1, s0
	s_bfe_i32 s0, s18, 0x80000
	s_and_b32 s18, s18, 0xf8
	s_sext_i32_i16 s19, s0
	s_sub_i32 s1, s1, s18
	s_lshl_b32 s7, s7, 3
	s_sext_i32_i8 s1, s1
	s_ashr_i32 s76, s19, 3
	s_add_i32 s30, s7, s1
	s_lshl_b32 s1, s76, 8
	s_lshr_b32 s0, s19, 3
	s_and_b32 s20, s1, 0xfffffe00
	s_lshr_b32 s6, s4, 6
	s_ashr_i32 s31, s30, 31
	s_ashr_i32 s21, s20, 31
	s_bfe_i64 s[0:1], s[0:1], 0x100000
	s_lshr_b32 s5, s4, 8
	s_lshl_b32 s44, s6, 10
	s_lshl_b64 s[18:19], s[30:31], 20
	s_lshl_b64 s[20:21], s[20:21], 1
	s_lshl_b64 s[0:1], s[0:1], 18
	s_add_u32 s36, s10, s0
	s_addc_u32 s37, s11, s1
	s_add_i32 s31, s44, 0
	s_add_i32 m0, s31, 0x10000
	v_lshl_or_b32 v152, v2, 10, v3
	global_load_lds_dwordx4 v148, s[36:37]
	s_add_i32 m0, s31, 0x12000
	s_add_u32 s7, s16, s18
	s_addc_u32 s18, s17, s19
	s_add_u32 s0, s36, 0x20000
	global_load_lds_dwordx4 v152, s[36:37]
	s_addc_u32 s1, s37, 0
	s_add_i32 m0, s31, 0x14000
	v_lshl_or_b32 v146, v6, 12, v3
	global_load_lds_dwordx4 v148, s[0:1]
	s_add_i32 m0, s31, 0x16000
	s_add_u32 s58, s7, s20
	s_addc_u32 s59, s18, s21
	s_add_i32 s45, s31, 0x2000
	global_load_lds_dwordx4 v152, s[0:1]
	s_mov_b32 m0, s31
	s_add_u32 s0, s58, 0x80000
	v_lshl_or_b32 v150, v5, 12, v3
	global_load_lds_dwordx4 v146, s[58:59]
	s_mov_b32 m0, s45
	s_addc_u32 s1, s59, 0
	s_add_i32 s54, s31, 0x4000
	global_load_lds_dwordx4 v150, s[58:59]
	s_mov_b32 m0, s54
	s_add_i32 s55, s31, 0x6000
	global_load_lds_dwordx4 v146, s[0:1]
	s_mov_b32 m0, s55
	v_mov_b32_e32 v149, 0
	global_load_lds_dwordx4 v150, s[0:1]
	v_mov_b32_e32 v153, v149
	v_mov_b32_e32 v147, v149
	v_mov_b32_e32 v151, v149
	s_cmp_eq_u32 s5, 1
	s_mov_b32 s62, 0
	v_lshl_add_u64 v[8:9], s[36:37], 0, v[148:149]
	v_lshl_add_u64 v[6:7], s[36:37], 0, v[152:153]
	v_lshl_add_u64 v[2:3], s[58:59], 0, v[146:147]
	s_cselect_b64 s[0:1], -1, 0
	s_cmp_lg_u32 s5, 1
	v_lshl_add_u64 v[4:5], s[58:59], 0, v[150:151]
	s_cbranch_scc1 .LBB0_466
	s_barrier
	s_setprio 1

; #define PG8_STAGE(bufoff, gbase, voff) do { _Pragma("unroll") for (int _i = 0; _i < 2; ++_i) \
;         __builtin_amdgcn_global_load_lds((const unsigned*)((const char*)(gbase) + (voff)[_i]), (PG8_LAS unsigned*)(lds + (bufoff) + ldsw + _i * 8192), 16, 0, 0); } while (0)
; #define PG8_BAR __builtin_amdgcn_s_barrier()
;     __host__ __device__ bool next(int i, Unit& u) const {
;         const long L = (long)i * G + c; if (L >= nwg) return false;
;         int wgid = (int)L; { const int q = nwg / NXCD, r = nwg % NXCD, xcd = wgid % NXCD, off = wgid / NXCD; wgid = (xcd < r ? xcd * (q + 1) : r * (q + 1) + (xcd - r) * q) + off; }
;         const int nig = WGM * nN, gid = wgid / nig, fm = gid * WGM, gsz = (nM - fm) < WGM ? (nM - fm) : WGM;
;         u.pm = fm + ((wgid % nig) % gsz); u.pn = (wgid % nig) / gsz; return true;
; template <class Epi, class Sched, bool ALIGN_EPI = false, bool SP2 = false>
; __device__ __forceinline__ void gemm_phase(PG8_LAS unsigned char* lds, const Gemm g, const Sched& S, const Epi& E) {
;     ...
;     for (int i = 0; i < 2; ++i) { int R, C; stage_rc(tid * 16 + i * 8192, R, C); const int Rb = Epi::PERM ? ((R & ~31) + perm32(R & 31)) : R;
;         voffA[i] = (unsigned)(R * g.lda + C) * 2u; voffB[i] = (unsigned)(Rb * g.ldb + C) * 2u; }
;     const size_t kstep = (size_t)(BK * 2);
;     const size_t hstepA = (size_t)HALF * g.lda * 2, hstepB = (size_t)HALF * g.ldb * 2;
;     const size_t tstepA = 2 * hstepA, tstepB = 2 * hstepB;
;     const unsigned ldsw = (unsigned)wid * 1024u;
;     const int aoff = lds_byte(wr * 64 + fr, fq * 8), boff = lds_byte(wc * 32 + fr, fq * 8);
;     ...
;     Unit cur, nxt; int ui = 0;
;     if (!S.next(0, cur)) return;
;     f32x4 acc[2][2][4][2];
; #pragma unroll
;     for (int a = 0; a < 2; ++a)
; #pragma unroll
;         for (int b = 0; b < 2; ++b)
; #pragma unroll
;             for (int m = 0; m < 4; ++m)
; #pragma unroll
;                 for (int n = 0; n < 2; ++n) acc[a][b][m][n] = (f32x4){0.f, 0.f, 0.f, 0.f};
;     bf16x8 At[4][2], B0[2][2], B1[2][2];
;     const char* cA = PG8_ABASE(cur); const char* cB = (const char*)g.Bt + (size_t)cur.pn * tstepB;
;     S.a_ready(cur);
;     if constexpr (SP2) {
;         PG8_STAGE(PG8_SB(0, 0), cB, voffB); PG8_STAGE(PG8_SB(0, 1), cB + hstepB, voffB); PG8_STAGE(PG8_SA(0, 0), cA, voffA); PG8_STAGE(PG8_SA(0, 1), cA + hstepA, voffA);
;         if (wr == 1) PG8_BAR;
.LBB0_715:
	v_lshrrev_b32_e32 v4, 1, v0
	v_lshrrev_b32_e32 v5, 5, v0
	v_lshlrev_b32_e32 v2, 4, v0
	v_and_b32_e32 v3, 32, v0
	v_and_b32_e32 v4, 24, v4
	v_and_b32_e32 v5, 4, v5
	v_bfe_u32 v6, v0, 2, 2
	s_waitcnt vmcnt(0)
	v_bfe_u32 v12, v0, 2, 4
	v_bitop3_b32 v10, v2, v3, 48 bitop3:0x6c
	v_and_b32_e32 v11, 64, v0
	v_or3_b32 v4, v5, v6, v4
	v_lshrrev_b32_e32 v5, 3, v0
	v_or_b32_e32 v13, 0x2000, v2
	s_ashr_i32 s0, s6, 3
	v_or_b32_e32 v3, v10, v11
	v_and_or_b32 v6, v5, 48, v12
	v_and_or_b32 v5, v5, 32, v4
	v_lshrrev_b32_e32 v2, 7, v13
	s_movk_i32 s1, 0x70
	v_lshl_or_b32 v136, v5, 13, v3
	v_and_or_b32 v5, v2, s1, v12
	s_movk_i32 s1, 0x60
	s_add_i32 s0, s4, s0
	v_and_or_b32 v2, v2, s1, v4
	s_ashr_i32 s1, s0, 31
	s_lshr_b32 s1, s1, 25
	s_add_i32 s1, s0, s1
	s_ashr_i32 s4, s1, 7
	s_and_b32 s1, s1, 0xffffff80
	s_sub_i32 s0, s0, s1
	s_bfe_i32 s1, s0, 0x80000
	s_bfe_u32 s1, s1, 0x3000c
	s_add_i32 s1, s0, s1
	s_lshl_b32 s6, s4, 3
	s_bfe_i32 s4, s1, 0x80000
	s_and_b32 s1, s1, 0xf8
	s_sub_i32 s0, s0, s1
	s_sext_i32_i16 s4, s4
	s_sext_i32_i8 s0, s0
	s_lshr_b32 s4, s4, 3
	s_add_i32 s0, s6, s0
	s_lshr_b32 s11, s5, 6
	s_ashr_i32 s1, s0, 31
	s_bfe_i64 s[8:9], s[4:5], 0x100000
	s_lshr_b32 s10, s5, 8
	s_lshl_b32 s33, s11, 10
	s_lshl_b64 s[6:7], s[0:1], 21
	s_lshl_b64 s[8:9], s[8:9], 21
	v_readlane_b32 s12, v244, 2
	v_readlane_b32 s13, v244, 3
	s_add_u32 s30, s12, s8
	s_addc_u32 s31, s13, s9
	s_add_i32 s44, s33, 0
	s_add_i32 m0, s44, 0x10000
	v_lshl_or_b32 v140, v2, 13, v3
	global_load_lds_dwordx4 v136, s[30:31]
	s_add_i32 m0, s44, 0x12000
	s_add_u32 s8, s30, 0x100000
	global_load_lds_dwordx4 v140, s[30:31]
	s_addc_u32 s9, s31, 0
	s_add_i32 m0, s44, 0x14000
	v_lshl_or_b32 v134, v6, 13, v3
	global_load_lds_dwordx4 v136, s[8:9]
	s_add_i32 m0, s44, 0x16000
	s_add_u32 s28, s56, s6
	s_addc_u32 s29, s57, s7
	s_add_i32 s45, s44, 0x2000
	global_load_lds_dwordx4 v140, s[8:9]
	s_mov_b32 m0, s44
	s_add_u32 s6, s28, 0x100000
	v_lshl_or_b32 v138, v5, 13, v3
	global_load_lds_dwordx4 v134, s[28:29]
	s_mov_b32 m0, s45
	s_addc_u32 s7, s29, 0
	s_add_i32 s54, s44, 0x4000
	global_load_lds_dwordx4 v138, s[28:29]
	s_mov_b32 m0, s54
	s_add_i32 s55, s44, 0x6000
	global_load_lds_dwordx4 v134, s[6:7]
	s_mov_b32 m0, s55
	v_mov_b32_e32 v137, 0
	global_load_lds_dwordx4 v138, s[6:7]
	v_mov_b32_e32 v141, v137
	v_mov_b32_e32 v135, v137
	v_mov_b32_e32 v139, v137
	s_cmp_eq_u32 s10, 1
	s_mov_b32 s58, 0
	v_lshl_add_u64 v[8:9], s[30:31], 0, v[136:137]
	v_lshl_add_u64 v[4:5], s[30:31], 0, v[140:141]
	s_mov_b64 s[6:7], 0x100000
	v_lshl_add_u64 v[2:3], s[28:29], 0, v[134:135]
	s_cselect_b64 s[8:9], -1, 0
	s_cmp_lg_u32 s10, 1
	v_lshl_add_u64 v[6:7], s[28:29], 0, v[138:139]
	s_cbranch_scc1 .LBB0_717
	s_barrier
	s_setprio 1

; #define PG8_STAGE(bufoff, gbase, voff) do { _Pragma("unroll") for (int _i = 0; _i < 2; ++_i) \
;         __builtin_amdgcn_global_load_lds((const unsigned*)((const char*)(gbase) + (voff)[_i]), (PG8_LAS unsigned*)(lds + (bufoff) + ldsw + _i * 8192), 16, 0, 0); } while (0)
; #define PG8_BAR __builtin_amdgcn_s_barrier()
;     __host__ __device__ bool next(int i, Unit& u) const {
;         const long L = (long)i * G + c; if (L >= nwg) return false;
;         int wgid = (int)L; { const int q = nwg / NXCD, r = nwg % NXCD, xcd = wgid % NXCD, off = wgid / NXCD; wgid = (xcd < r ? xcd * (q + 1) : r * (q + 1) + (xcd - r) * q) + off; }
;         const int nig = WGM * nN, gid = wgid / nig, fm = gid * WGM, gsz = (nM - fm) < WGM ? (nM - fm) : WGM;
;         u.pm = fm + ((wgid % nig) % gsz); u.pn = (wgid % nig) / gsz; return true;
; template <class Epi, class Sched, bool ALIGN_EPI = false, bool SP2 = false>
; __device__ __forceinline__ void gemm_phase(PG8_LAS unsigned char* lds, const Gemm g, const Sched& S, const Epi& E) {
;     ...
;     for (int i = 0; i < 2; ++i) { int R, C; stage_rc(tid * 16 + i * 8192, R, C); const int Rb = Epi::PERM ? ((R & ~31) + perm32(R & 31)) : R;
;         voffA[i] = (unsigned)(R * g.lda + C) * 2u; voffB[i] = (unsigned)(Rb * g.ldb + C) * 2u; }
;     const size_t kstep = (size_t)(BK * 2);
;     const size_t hstepA = (size_t)HALF * g.lda * 2, hstepB = (size_t)HALF * g.ldb * 2;
;     const size_t tstepA = 2 * hstepA, tstepB = 2 * hstepB;
;     const unsigned ldsw = (unsigned)wid * 1024u;
;     const int aoff = lds_byte(wr * 64 + fr, fq * 8), boff = lds_byte(wc * 32 + fr, fq * 8);
;     ...
;     Unit cur, nxt; int ui = 0;
;     if (!S.next(0, cur)) return;
;     f32x4 acc[2][2][4][2];
; #pragma unroll
;     for (int a = 0; a < 2; ++a)
; #pragma unroll
;         for (int b = 0; b < 2; ++b)
; #pragma unroll
;             for (int m = 0; m < 4; ++m)
; #pragma unroll
;                 for (int n = 0; n < 2; ++n) acc[a][b][m][n] = (f32x4){0.f, 0.f, 0.f, 0.f};
;     bf16x8 At[4][2], B0[2][2], B1[2][2];
;     const char* cA = PG8_ABASE(cur); const char* cB = (const char*)g.Bt + (size_t)cur.pn * tstepB;
;     S.a_ready(cur);
;     if constexpr (SP2) {
;         PG8_STAGE(PG8_SB(0, 0), cB, voffB); PG8_STAGE(PG8_SB(0, 1), cB + hstepB, voffB); PG8_STAGE(PG8_SA(0, 0), cA, voffA); PG8_STAGE(PG8_SA(0, 1), cA + hstepA, voffA);
;         if (wr == 1) PG8_BAR;
.LBB0_796:
	v_lshrrev_b32_e32 v5, 1, v0
	v_lshrrev_b32_e32 v6, 5, v0
	v_lshlrev_b32_e32 v2, 4, v0
	v_and_b32_e32 v3, 32, v0
	v_and_b32_e32 v5, 24, v5
	v_and_b32_e32 v6, 4, v6
	v_bfe_u32 v7, v0, 2, 2
	s_waitcnt vmcnt(0)
	v_bfe_u32 v13, v0, 2, 4
	v_bitop3_b32 v3, v2, v3, 48 bitop3:0x6c
	v_and_b32_e32 v12, 64, v0
	v_or3_b32 v5, v6, v7, v5
	v_lshrrev_b32_e32 v6, 3, v0
	v_or_b32_e32 v14, 0x2000, v2
	s_ashr_i32 s0, s6, 3
	v_or_b32_e32 v4, v3, v12
	v_and_or_b32 v7, v6, 48, v13
	v_and_or_b32 v6, v6, 32, v5
	v_lshrrev_b32_e32 v2, 7, v14
	s_movk_i32 s1, 0x70
	v_lshl_or_b32 v166, v6, 13, v4
	v_and_or_b32 v6, v2, s1, v13
	s_movk_i32 s1, 0x60
	s_add_i32 s0, s4, s0
	v_and_or_b32 v2, v2, s1, v5
	s_ashr_i32 s1, s0, 31
	s_lshr_b32 s1, s1, 25
	s_add_i32 s1, s0, s1
	s_ashr_i32 s4, s1, 7
	s_and_b32 s1, s1, 0xffffff80
	s_sub_i32 s0, s0, s1
	s_bfe_i32 s1, s0, 0x80000
	s_bfe_u32 s1, s1, 0x3000c
	s_add_i32 s1, s0, s1
	s_lshl_b32 s10, s4, 3
	s_bfe_i32 s4, s1, 0x80000
	s_and_b32 s1, s1, 0xf8
	s_sub_i32 s0, s0, s1
	s_sext_i32_i16 s4, s4
	s_sext_i32_i8 s0, s0
	s_lshr_b32 s4, s4, 3
	s_add_i32 s30, s10, s0
	s_lshr_b32 s6, s5, 6
	s_ashr_i32 s31, s30, 31
	s_bfe_i64 s[10:11], s[4:5], 0x100000
	s_lshr_b32 s7, s5, 8
	s_lshl_b32 s33, s6, 10
	s_lshl_b64 s[0:1], s[30:31], 21
	s_lshl_b64 s[10:11], s[10:11], 21
	v_readlane_b32 s12, v244, 4
	v_readlane_b32 s13, v244, 5
	s_add_u32 s36, s12, s10
	s_addc_u32 s37, s13, s11
	s_add_i32 s42, s33, 0
	s_add_i32 m0, s42, 0x10000
	v_lshl_or_b32 v170, v2, 13, v4
	global_load_lds_dwordx4 v166, s[36:37]
	s_add_i32 m0, s42, 0x12000
	s_add_u32 s10, s36, 0x100000
	global_load_lds_dwordx4 v170, s[36:37]
	s_addc_u32 s11, s37, 0
	s_add_i32 m0, s42, 0x14000
	v_lshl_or_b32 v164, v7, 13, v4
	global_load_lds_dwordx4 v166, s[10:11]
	s_add_i32 m0, s42, 0x16000
	s_add_u32 s28, s38, s0
	s_addc_u32 s29, s39, s1
	s_add_i32 s43, s42, 0x2000
	global_load_lds_dwordx4 v170, s[10:11]
	s_mov_b32 m0, s42
	s_add_u32 s0, s28, 0x100000
	v_lshl_or_b32 v168, v6, 13, v4
	global_load_lds_dwordx4 v164, s[28:29]
	s_mov_b32 m0, s43
	s_addc_u32 s1, s29, 0
	s_add_i32 s44, s42, 0x4000
	global_load_lds_dwordx4 v168, s[28:29]
	s_mov_b32 m0, s44
	s_add_i32 s45, s42, 0x6000
	global_load_lds_dwordx4 v164, s[0:1]
	s_mov_b32 m0, s45
	v_mov_b32_e32 v2, 0
	global_load_lds_dwordx4 v168, s[0:1]
	v_mov_b32_e32 v167, v2
	v_mov_b32_e32 v171, v2
	v_mov_b32_e32 v165, v2
	v_mov_b32_e32 v169, v2
	s_cmp_eq_u32 s7, 1
	s_mov_b32 s54, 0
	v_lshl_add_u64 v[10:11], s[36:37], 0, v[166:167]
	v_lshl_add_u64 v[6:7], s[36:37], 0, v[170:171]
	v_lshl_add_u64 v[4:5], s[28:29], 0, v[164:165]
	s_cselect_b64 s[0:1], -1, 0
	s_cmp_lg_u32 s7, 1
	v_lshl_add_u64 v[8:9], s[28:29], 0, v[168:169]
	s_cbranch_scc1 .LBB0_798
	s_barrier
	s_setprio 1

; #define PG8_STAGE(bufoff, gbase, voff) do { _Pragma("unroll") for (int _i = 0; _i < 2; ++_i) \
;         __builtin_amdgcn_global_load_lds((const unsigned*)((const char*)(gbase) + (voff)[_i]), (PG8_LAS unsigned*)(lds + (bufoff) + ldsw + _i * 8192), 16, 0, 0); } while (0)
; #define PG8_BAR __builtin_amdgcn_s_barrier()
;     __host__ __device__ bool next(int i, Unit& u) const {
;         const long L = (long)i * G + c; if (L >= nwg) return false;
;         int wgid = (int)L; { const int q = nwg / NXCD, r = nwg % NXCD, xcd = wgid % NXCD, off = wgid / NXCD; wgid = (xcd < r ? xcd * (q + 1) : r * (q + 1) + (xcd - r) * q) + off; }
;         const int nig = WGM * nN, gid = wgid / nig, fm = gid * WGM, gsz = (nM - fm) < WGM ? (nM - fm) : WGM;
;         u.pm = fm + ((wgid % nig) % gsz); u.pn = (wgid % nig) / gsz; return true;
; template <class Epi, class Sched, bool ALIGN_EPI = false, bool SP2 = false>
; __device__ __forceinline__ void gemm_phase(PG8_LAS unsigned char* lds, const Gemm g, const Sched& S, const Epi& E) {
;     ...
;     for (int i = 0; i < 2; ++i) { int R, C; stage_rc(tid * 16 + i * 8192, R, C); const int Rb = Epi::PERM ? ((R & ~31) + perm32(R & 31)) : R;
;         voffA[i] = (unsigned)(R * g.lda + C) * 2u; voffB[i] = (unsigned)(Rb * g.ldb + C) * 2u; }
;     const size_t kstep = (size_t)(BK * 2);
;     const size_t hstepA = (size_t)HALF * g.lda * 2, hstepB = (size_t)HALF * g.ldb * 2;
;     const size_t tstepA = 2 * hstepA, tstepB = 2 * hstepB;
;     const unsigned ldsw = (unsigned)wid * 1024u;
;     const int aoff = lds_byte(wr * 64 + fr, fq * 8), boff = lds_byte(wc * 32 + fr, fq * 8);
;     ...
;     Unit cur, nxt; int ui = 0;
;     if (!S.next(0, cur)) return;
;     f32x4 acc[2][2][4][2];
; #pragma unroll
;     for (int a = 0; a < 2; ++a)
; #pragma unroll
;         for (int b = 0; b < 2; ++b)
; #pragma unroll
;             for (int m = 0; m < 4; ++m)
; #pragma unroll
;                 for (int n = 0; n < 2; ++n) acc[a][b][m][n] = (f32x4){0.f, 0.f, 0.f, 0.f};
;     bf16x8 At[4][2], B0[2][2], B1[2][2];
;     const char* cA = PG8_ABASE(cur); const char* cB = (const char*)g.Bt + (size_t)cur.pn * tstepB;
;     S.a_ready(cur);
;     if constexpr (SP2) {
;         PG8_STAGE(PG8_SB(0, 0), cB, voffB); PG8_STAGE(PG8_SB(0, 1), cB + hstepB, voffB); PG8_STAGE(PG8_SA(0, 0), cA, voffA); PG8_STAGE(PG8_SA(0, 1), cA + hstepA, voffA);
;         if (wr == 1) PG8_BAR;
.LBB0_899:
	s_andn2_b64 vcc, exec, s[0:1]
	v_readfirstlane_b32 s1, v0
	s_waitcnt vmcnt(0) lgkmcnt(0)
	s_barrier
	s_cbranch_vccnz .LBB0_915
	v_lshrrev_b32_e32 v2, 5, v0
	v_lshrrev_b32_e32 v4, 1, v0
	v_and_b32_e32 v2, 4, v2
	v_bfe_u32 v3, v0, 2, 2
	v_and_b32_e32 v13, 24, v4
	v_or3_b32 v2, v2, v3, v13
	v_lshlrev_b32_e32 v3, 4, v0
	v_or_b32_e32 v10, 0x2000, v3
	v_lshrrev_b32_e32 v4, 7, v10
	s_movk_i32 s0, 0x60
	v_and_or_b32 v5, v4, s0, v2
	v_bfe_u32 v14, v0, 2, 4
	s_movk_i32 s0, 0x70
	v_and_or_b32 v4, v4, s0, v14
	s_lshr_b32 s0, s3, 29
	s_add_i32 s0, s2, s0
	s_lshr_b32 s5, s1, 6
	s_ashr_i32 s6, s0, 3
	s_and_b32 s0, s0, -8
	s_lshr_b32 s4, s1, 8
	s_lshl_b32 s30, s5, 10
	s_sub_i32 s0, s2, s0
	s_cmp_lt_i32 s0, 0
	s_movk_i32 s31, 0x159
	s_cselect_b32 s7, s31, 0x158
	s_mul_i32 s0, s0, s7
	s_add_i32 s0, s0, s6
	s_mul_hi_i32 s6, s0, 0x2fa0be83
	s_lshr_b32 s7, s6, 31
	s_ashr_i32 s6, s6, 7
	s_add_i32 s6, s6, s7
	s_lshl_b32 s7, s6, 3
	s_mulk_i32 s6, 0x2b0
	s_sub_i32 s6, s0, s6
	s_bfe_u32 s0, s6, 0x3001c
	s_add_i32 s12, s6, s0
	s_sext_i32_i16 s0, s12
	s_and_b32 s12, s12, 0xfff8
	s_sub_i32 s6, s6, s12
	s_sext_i32_i16 s6, s6
	v_and_b32_e32 v6, 32, v0
	s_lshr_b32 s0, s0, 3
	s_add_i32 s22, s7, s6
	v_bitop3_b32 v11, v3, v6, 48 bitop3:0x6c
	v_and_b32_e32 v12, 64, v0
	s_ashr_i32 s23, s22, 31
	s_bfe_i64 s[12:13], s[0:1], 0x100000
	v_or_b32_e32 v3, v11, v12
	s_lshl_b64 s[6:7], s[22:23], 21
	s_lshl_b64 s[12:13], s[12:13], 21
	v_lshl_or_b32 v132, v4, 13, v3
	v_lshrrev_b32_e32 v4, 3, v0
	s_add_u32 s26, s60, s12
	v_and_or_b32 v2, v4, 32, v2
	s_addc_u32 s27, s61, s13
	s_add_i32 s23, s30, 0
	v_lshl_or_b32 v134, v2, 13, v3
	s_add_i32 m0, s23, 0x10000
	v_lshl_or_b32 v130, v5, 13, v3
	global_load_lds_dwordx4 v134, s[26:27]
	s_add_i32 m0, s23, 0x12000
	s_add_u32 s12, s26, 0x100000
	global_load_lds_dwordx4 v130, s[26:27]
	s_addc_u32 s13, s27, 0
	s_add_i32 m0, s23, 0x14000
	v_and_or_b32 v2, v4, 48, v14
	global_load_lds_dwordx4 v134, s[12:13]
	s_add_i32 m0, s23, 0x16000
	s_add_u32 s24, s8, s6
	s_addc_u32 s25, s9, s7
	s_add_i32 s33, s23, 0x2000
	v_lshl_or_b32 v136, v2, 13, v3
	global_load_lds_dwordx4 v130, s[12:13]
	s_mov_b32 m0, s23
	s_add_u32 s6, s24, 0x100000
	global_load_lds_dwordx4 v136, s[24:25]
	s_mov_b32 m0, s33
	s_addc_u32 s7, s25, 0
	s_add_i32 s36, s23, 0x4000
	global_load_lds_dwordx4 v132, s[24:25]
	s_mov_b32 m0, s36
	s_add_i32 s37, s23, 0x6000
	global_load_lds_dwordx4 v136, s[6:7]
	s_mov_b32 m0, s37
	v_mov_b32_e32 v135, 0
	global_load_lds_dwordx4 v132, s[6:7]
	v_mov_b32_e32 v131, v135
	v_mov_b32_e32 v137, v135
	v_mov_b32_e32 v133, v135
	s_cmp_eq_u32 s4, 1
	s_mov_b32 s38, 0
	v_lshl_add_u64 v[8:9], s[26:27], 0, v[134:135]
	v_lshl_add_u64 v[6:7], s[26:27], 0, v[130:131]
	v_lshl_add_u64 v[2:3], s[24:25], 0, v[136:137]
	s_cselect_b64 s[6:7], -1, 0
	s_cmp_lg_u32 s4, 1
	v_lshl_add_u64 v[4:5], s[24:25], 0, v[132:133]
	s_cbranch_scc1 .LBB0_902
	s_barrier
	s_setprio 1

; #define PG8_STAGE(bufoff, gbase, voff) do { _Pragma("unroll") for (int _i = 0; _i < 2; ++_i) \
;         __builtin_amdgcn_global_load_lds((const unsigned*)((const char*)(gbase) + (voff)[_i]), (PG8_LAS unsigned*)(lds + (bufoff) + ldsw + _i * 8192), 16, 0, 0); } while (0)
; #define PG8_BAR __builtin_amdgcn_s_barrier()
;     __device__ __forceinline__ bool next(int i, Unit& u) const { if (i != 0) return false; u.pm = pm; u.pn = pn; return true; }
; template <class Epi, class Sched, bool ALIGN_EPI = false, bool SP2 = false>
; __device__ __forceinline__ void gemm_phase(PG8_LAS unsigned char* lds, const Gemm g, const Sched& S, const Epi& E) {
;     ...
;     for (int i = 0; i < 2; ++i) { int R, C; stage_rc(tid * 16 + i * 8192, R, C); const int Rb = Epi::PERM ? ((R & ~31) + perm32(R & 31)) : R;
;         voffA[i] = (unsigned)(R * g.lda + C) * 2u; voffB[i] = (unsigned)(Rb * g.ldb + C) * 2u; }
;     const size_t kstep = (size_t)(BK * 2);
;     const size_t hstepA = (size_t)HALF * g.lda * 2, hstepB = (size_t)HALF * g.ldb * 2;
;     const size_t tstepA = 2 * hstepA, tstepB = 2 * hstepB;
;     const unsigned ldsw = (unsigned)wid * 1024u;
;     const int aoff = lds_byte(wr * 64 + fr, fq * 8), boff = lds_byte(wc * 32 + fr, fq * 8);
;     ...
;     Unit cur, nxt; int ui = 0;
;     if (!S.next(0, cur)) return;
;     f32x4 acc[2][2][4][2];
; #pragma unroll
;     for (int a = 0; a < 2; ++a)
; #pragma unroll
;         for (int b = 0; b < 2; ++b)
; #pragma unroll
;             for (int m = 0; m < 4; ++m)
; #pragma unroll
;                 for (int n = 0; n < 2; ++n) acc[a][b][m][n] = (f32x4){0.f, 0.f, 0.f, 0.f};
;     bf16x8 At[4][2], B0[2][2], B1[2][2];
;     const char* cA = PG8_ABASE(cur); const char* cB = (const char*)g.Bt + (size_t)cur.pn * tstepB;
;     S.a_ready(cur);
;     if constexpr (SP2) {
;         PG8_STAGE(PG8_SB(0, 0), cB, voffB); PG8_STAGE(PG8_SB(0, 1), cB + hstepB, voffB); PG8_STAGE(PG8_SA(0, 0), cA, voffA); PG8_STAGE(PG8_SA(0, 1), cA + hstepA, voffA);
;         if (wr == 1) PG8_BAR;
.LBB0_970:
	s_cmp_lt_i32 s70, 10
	s_cselect_b64 s[0:1], -1, 0
	s_cmp_gt_i32 s71, 9
	s_cselect_b64 s[4:5], -1, 0
	s_and_b64 s[0:1], s[0:1], s[4:5]
	s_andn2_b64 vcc, exec, s[0:1]
	s_cbranch_vccnz .LBB0_1059
	s_andn2_b64 vcc, exec, s[34:35]
	s_cbranch_vccnz .LBB0_1059
	v_lshlrev_b32_e32 v2, 4, v0
	v_and_b32_e32 v3, 32, v0
	v_bitop3_b32 v6, v2, v3, 48 bitop3:0x6c
	v_lshrrev_b32_e32 v3, 1, v0
	v_lshrrev_b32_e32 v5, 5, v0
	v_and_b32_e32 v3, 24, v3
	v_and_b32_e32 v5, 4, v5
	v_bfe_u32 v8, v0, 2, 2
	v_bfe_u32 v4, v0, 2, 4
	v_and_b32_e32 v7, 64, v0
	v_or3_b32 v3, v5, v8, v3
	v_lshrrev_b32_e32 v5, 3, v0
	s_lshl_b32 s0, s2, 1
	v_or_b32_e32 v2, v6, v7
	v_and_or_b32 v8, v5, 48, v4
	v_and_or_b32 v5, v5, 32, v3
	s_and_b32 s34, s0, 12
	s_lshl_b32 s0, s2, 3
	v_lshrrev_b32_e32 v2, 1, v2
	v_mul_u32_u24_e32 v5, 0x2b00, v5
	s_and_b32 s0, s0, 8
	s_ashr_i32 s1, s2, 5
	v_readfirstlane_b32 s40, v0
	v_or_b32_e32 v5, v5, v2
	s_bfe_u32 s35, s2, 0x20003
	s_add_i32 s6, s0, s1
	s_lshr_b32 s41, s40, 6
	v_lshlrev_b32_e32 v174, 1, v5
	v_bfe_u32 v5, v0, 3, 25
	s_or_b32 s36, s34, s35
	s_lshr_b32 s3, s40, 8
	v_or_b32_e32 v5, 64, v5
	s_movk_i32 s0, 0x70
	s_lshl_b32 s28, s41, 10
	s_ashr_i32 s7, s6, 31
	s_mul_i32 s13, s6, 0x560000
	v_mul_u32_u24_e32 v8, 0x2b00, v8
	v_and_or_b32 v4, v5, s0, v4
	s_movk_i32 s0, 0x60
	s_mul_hi_i32 s12, s6, 0x560000
	s_add_u32 s10, s10, s13
	v_or_b32_e32 v9, v2, v8
	v_and_or_b32 v3, v5, s0, v3
	s_addc_u32 s11, s11, s12
	s_add_i32 s42, s28, 0
	v_lshlrev_b32_e32 v172, 1, v9
	v_mul_u32_u24_e32 v9, 0x2b00, v4
	v_mul_u32_u24_e32 v3, 0x2b00, v3
	s_add_i32 m0, s42, 0x10000
	v_or_b32_e32 v4, v9, v2
	v_or_b32_e32 v2, v3, v2
	global_load_lds_dwordx4 v174, s[10:11]
	s_add_i32 m0, s42, 0x12000
	v_lshlrev_b32_e32 v178, 1, v2
	s_add_u32 s4, s10, 0x2b0000
	global_load_lds_dwordx4 v178, s[10:11]
	s_addc_u32 s5, s11, 0
	s_add_i32 m0, s42, 0x14000
	s_mul_i32 s0, s36, 0x560000
	global_load_lds_dwordx4 v174, s[4:5]
	s_add_i32 m0, s42, 0x16000
	v_readlane_b32 s14, v244, 11
	v_readlane_b32 s15, v244, 12
	s_add_u32 s0, s14, s0
	s_addc_u32 s1, s15, 0
	s_add_i32 s54, s42, 0x2000
	global_load_lds_dwordx4 v178, s[4:5]
	s_mov_b32 m0, s42
	s_add_u32 s14, s0, 0x2b0000
	v_lshlrev_b32_e32 v176, 1, v4
	global_load_lds_dwordx4 v172, s[0:1]
	s_mov_b32 m0, s54
	s_addc_u32 s15, s1, 0
	s_add_i32 s55, s42, 0x4000
	global_load_lds_dwordx4 v176, s[0:1]
	s_mov_b32 m0, s55
	s_add_i32 s56, s42, 0x6000
	global_load_lds_dwordx4 v172, s[14:15]
	s_mov_b32 m0, s56
	v_mov_b32_e32 v175, 0
	global_load_lds_dwordx4 v176, s[14:15]
	v_mov_b32_e32 v179, v175
	v_mov_b32_e32 v173, v175
	v_mov_b32_e32 v177, v175
	v_lshl_add_u64 v[190:191], s[10:11], 0, v[174:175]
	v_lshl_add_u64 v[188:189], s[10:11], 0, v[178:179]
	v_lshl_add_u64 v[4:5], s[0:1], 0, v[172:173]
	s_cmp_lg_u32 s3, 1
	v_lshl_add_u64 v[2:3], s[0:1], 0, v[176:177]
	s_cbranch_scc1 .LBB0_974
	s_barrier
	s_setprio 1

;     __device__ __forceinline__ void fused(f32x4 (&acc)[2][2][4][2], const Unit& u, int wr, int wc, int fr, int fq, PG8_LAS unsigned char* lds, int wid, int lane) const {
;     ...
;         asm volatile("s_waitcnt lgkmcnt(0)" ::: "memory"); __builtin_amdgcn_s_barrier(); asm volatile("" ::: "memory");
;         f32x4 gv[2][2];
; #pragma unroll
;         for (int bj = 0; bj < 2; ++bj)
; #pragma unroll
;             for (int n = 0; n < 2; ++n) gv[bj][n] = *(const f32x4*)(gain + col0 + bj * HALF + 4 * n);
; #pragma unroll
;         for (int ai = 0; ai < 2; ++ai)
; #pragma unroll
;             for (int m = 0; m < 4; ++m) { const int rl = ai * HALF + wr * 64 + m * 16 + fr; const float rs = Sx[rl]; const size_t ro = (size_t)(u.pm * BM + rl) * D + col0;
; #pragma unroll
;                 for (int bj = 0; bj < 2; ++bj) { *(f32x4*)(O + ro + bj * HALF) = acc[ai][bj][m][0] * rs * gv[bj][0]; *(f32x4*)(O + ro + bj * HALF + 4) = acc[ai][bj][m][1] * rs * gv[bj][1]; } }
.LBB0_1015:
	s_or_b64 exec, exec, s[16:17]
	v_lshl_or_b32 v207, v203, 3, s37
	v_or_b32_e32 v2, s38, v207
	v_ashrrev_i32_e32 v3, 31, v2
	v_lshlrev_b64 v[148:149], 2, v[2:3]
	s_waitcnt lgkmcnt(0)
	s_barrier
	v_lshl_add_u64 v[2:3], s[48:49], 0, v[148:149]
	global_load_dwordx4 v[144:147], v[2:3], off
	global_load_dwordx4 v[140:143], v[2:3], off offset:16
	global_load_dwordx4 v[136:139], v[2:3], off offset:512
	s_waitcnt lgkmcnt(0)
	global_load_dwordx4 v[132:135], v[2:3], off offset:528
	v_lshl_add_u32 v1, v208, 2, 0
	v_add_u32_e32 v1, 0x1000, v1
	ds_read2_b32 v[156:157], v1 offset1:16
	ds_read2_b32 v[158:159], v1 offset0:32 offset1:48
	v_add_u32_e32 v2, s39, v208
	v_mov_b32_e32 v3, 0
	v_add_u32_e32 v154, 32, v2
	v_mov_b32_e32 v155, v3
	v_lshlrev_b64 v[150:151], 14, v[2:3]
	v_add_u32_e32 v152, 16, v2
	v_mov_b32_e32 v153, v3
	v_lshlrev_b64 v[154:155], 14, v[154:155]
	v_lshl_add_u64 v[150:151], s[50:51], 0, v[150:151]
	v_lshlrev_b64 v[152:153], 14, v[152:153]
	v_lshl_add_u64 v[154:155], s[50:51], 0, v[154:155]
	s_waitcnt lgkmcnt(0)
	v_pk_mul_f32 v[128:129], v[128:129], v[156:157] op_sel_hi:[1,0]
	v_pk_mul_f32 v[130:131], v[130:131], v[156:157] op_sel_hi:[1,0]
	v_pk_mul_f32 v[124:125], v[124:125], v[156:157] op_sel_hi:[1,0]
	v_pk_mul_f32 v[126:127], v[126:127], v[156:157] op_sel_hi:[1,0]
	v_pk_mul_f32 v[120:121], v[120:121], v[156:157] op_sel_hi:[1,0]
	v_pk_mul_f32 v[122:123], v[122:123], v[156:157] op_sel_hi:[1,0]
	v_pk_mul_f32 v[116:117], v[116:117], v[156:157] op_sel_hi:[1,0]
	v_pk_mul_f32 v[118:119], v[118:119], v[156:157] op_sel_hi:[1,0]
	v_mov_b32_e32 v156, v157
	v_pk_mul_f32 v[84:85], v[84:85], v[158:159] op_sel_hi:[1,0]
	v_pk_mul_f32 v[86:87], v[86:87], v[158:159] op_sel_hi:[1,0]
	v_lshl_add_u64 v[152:153], s[50:51], 0, v[152:153]
	v_lshl_add_u64 v[150:151], v[150:151], 0, v[148:149]
	v_lshl_add_u64 v[154:155], v[154:155], 0, v[148:149]
	v_pk_mul_f32 v[160:161], v[112:113], v[158:159] op_sel_hi:[1,0]
	v_pk_mul_f32 v[162:163], v[114:115], v[158:159] op_sel_hi:[1,0]
	v_pk_mul_f32 v[164:165], v[108:109], v[158:159] op_sel_hi:[1,0]
	v_pk_mul_f32 v[166:167], v[110:111], v[158:159] op_sel_hi:[1,0]
	v_pk_mul_f32 v[168:169], v[104:105], v[158:159] op_sel_hi:[1,0]
	v_pk_mul_f32 v[170:171], v[106:107], v[158:159] op_sel_hi:[1,0]
	v_pk_mul_f32 v[104:105], v[100:101], v[156:157] op_sel_hi:[1,0]
	v_pk_mul_f32 v[106:107], v[102:103], v[156:157] op_sel_hi:[1,0]
	v_pk_mul_f32 v[108:109], v[96:97], v[156:157] op_sel_hi:[1,0]
	v_pk_mul_f32 v[110:111], v[98:99], v[156:157] op_sel_hi:[1,0]
	v_pk_mul_f32 v[112:113], v[92:93], v[156:157] op_sel_hi:[1,0]
	v_pk_mul_f32 v[114:115], v[94:95], v[156:157] op_sel_hi:[1,0]
	v_pk_mul_f32 v[208:209], v[88:89], v[156:157] op_sel_hi:[1,0]
	v_pk_mul_f32 v[156:157], v[90:91], v[156:157] op_sel_hi:[1,0]
	v_lshl_add_u64 v[152:153], v[152:153], 0, v[148:149]
	v_readfirstlane_b32 s56, v0
	s_lshr_b32 s57, s56, 6
	s_lshl_b32 s40, s57, 10
	s_add_i32 s58, s40, 0
	s_add_i32 m0, s58, 0x10000
	s_or_b32 s20, s36, 16
	s_lshr_b32 s18, s56, 8
	s_mul_i32 s16, s20, 0x560000
	s_waitcnt vmcnt(0)
	v_pk_mul_f32 v[90:91], v[146:147], v[130:131]
	v_pk_mul_f32 v[88:89], v[144:145], v[128:129]
	v_pk_mul_f32 v[94:95], v[142:143], v[126:127]
	v_pk_mul_f32 v[86:87], v[134:135], v[86:87]
	v_pk_mul_f32 v[84:85], v[132:133], v[84:85]
	v_pk_mul_f32 v[92:93], v[140:141], v[124:125]
	v_pk_mul_f32 v[98:99], v[138:139], v[122:123]
	v_pk_mul_f32 v[96:97], v[136:137], v[120:121]
	v_pk_mul_f32 v[102:103], v[134:135], v[118:119]
	v_pk_mul_f32 v[100:101], v[132:133], v[116:117]
	v_pk_mul_f32 v[106:107], v[146:147], v[106:107]
	v_pk_mul_f32 v[104:105], v[144:145], v[104:105]
	v_pk_mul_f32 v[110:111], v[142:143], v[110:111]
	v_pk_mul_f32 v[108:109], v[140:141], v[108:109]
	v_pk_mul_f32 v[114:115], v[138:139], v[114:115]
	v_pk_mul_f32 v[112:113], v[136:137], v[112:113]
	v_pk_mul_f32 v[118:119], v[134:135], v[156:157]
	v_pk_mul_f32 v[116:117], v[132:133], v[208:209]
	v_pk_mul_f32 v[122:123], v[146:147], v[162:163]
	v_pk_mul_f32 v[120:121], v[144:145], v[160:161]
	v_pk_mul_f32 v[126:127], v[142:143], v[166:167]
	v_pk_mul_f32 v[124:125], v[140:141], v[164:165]
	v_pk_mul_f32 v[130:131], v[138:139], v[170:171]
	v_pk_mul_f32 v[128:129], v[136:137], v[168:169]
	global_store_dwordx4 v[150:151], v[88:91], off
	global_store_dwordx4 v[150:151], v[92:95], off offset:16
	global_store_dwordx4 v[150:151], v[96:99], off offset:512
	global_store_dwordx4 v[150:151], v[100:103], off offset:528
	global_store_dwordx4 v[152:153], v[104:107], off
	global_store_dwordx4 v[152:153], v[108:111], off offset:16
	global_store_dwordx4 v[152:153], v[112:115], off offset:512
	global_store_dwordx4 v[152:153], v[116:119], off offset:528
	global_store_dwordx4 v[154:155], v[120:123], off
	global_store_dwordx4 v[154:155], v[124:127], off offset:16
	global_store_dwordx4 v[154:155], v[128:131], off offset:512
	global_store_dwordx4 v[154:155], v[84:87], off offset:528
	s_nop 1
	v_add_u32_e32 v84, 48, v2
	v_mov_b32_e32 v85, v3
	v_mov_b32_e32 v86, v159
	v_lshlrev_b64 v[84:85], 14, v[84:85]
	v_lshl_add_u64 v[84:85], s[50:51], 0, v[84:85]
	v_pk_mul_f32 v[72:73], v[72:73], v[86:87] op_sel_hi:[1,0]
	v_pk_mul_f32 v[74:75], v[74:75], v[86:87] op_sel_hi:[1,0]
	v_lshl_add_u64 v[84:85], v[84:85], 0, v[148:149]
	v_pk_mul_f32 v[74:75], v[138:139], v[74:75]
	v_pk_mul_f32 v[72:73], v[136:137], v[72:73]
	global_store_dwordx4 v[84:85], v[72:75], off offset:512
	ds_read2_b32 v[72:73], v1 offset0:128 offset1:144
	v_pk_mul_f32 v[68:69], v[68:69], v[86:87] op_sel_hi:[1,0]
	v_pk_mul_f32 v[70:71], v[70:71], v[86:87] op_sel_hi:[1,0]
	v_pk_mul_f32 v[68:69], v[132:133], v[68:69]
	v_pk_mul_f32 v[70:71], v[134:135], v[70:71]
	global_store_dwordx4 v[84:85], v[68:71], off offset:528
	s_waitcnt lgkmcnt(0)
; #define PG8_STAGE(bufoff, gbase, voff) do { _Pragma("unroll") for (int _i = 0; _i < 2; ++_i) \
;         __builtin_amdgcn_global_load_lds((const unsigned*)((const char*)(gbase) + (voff)[_i]), (PG8_LAS unsigned*)(lds + (bufoff) + ldsw + _i * 8192), 16, 0, 0); } while (0)
; #define PG8_BAR __builtin_amdgcn_s_barrier()
; template <class Epi, class Sched, bool ALIGN_EPI = false, bool SP2 = false>
; __device__ __forceinline__ void gemm_phase(PG8_LAS unsigned char* lds, const Gemm g, const Sched& S, const Epi& E) {
;     ...
;     const char* cA = PG8_ABASE(cur); const char* cB = (const char*)g.Bt + (size_t)cur.pn * tstepB;
;     S.a_ready(cur);
;     if constexpr (SP2) {
;         PG8_STAGE(PG8_SB(0, 0), cB, voffB); PG8_STAGE(PG8_SB(0, 1), cB + hstepB, voffB); PG8_STAGE(PG8_SA(0, 0), cA, voffA); PG8_STAGE(PG8_SA(0, 1), cA + hstepA, voffA);
;         if (wr == 1) PG8_BAR;
;     __device__ __forceinline__ void fused(f32x4 (&acc)[2][2][4][2], const Unit& u, int wr, int wc, int fr, int fq, PG8_LAS unsigned char* lds, int wid, int lane) const {
;     ...
;         for (int ai = 0; ai < 2; ++ai)
; #pragma unroll
;             for (int m = 0; m < 4; ++m) { const int rl = ai * HALF + wr * 64 + m * 16 + fr; const float rs = Sx[rl]; const size_t ro = (size_t)(u.pm * BM + rl) * D + col0;
; #pragma unroll
;                 for (int bj = 0; bj < 2; ++bj) { *(f32x4*)(O + ro + bj * HALF) = acc[ai][bj][m][0] * rs * gv[bj][0]; *(f32x4*)(O + ro + bj * HALF + 4) = acc[ai][bj][m][1] * rs * gv[bj][1]; } }
	v_pk_mul_f32 v[52:53], v[52:53], v[72:73] op_sel_hi:[1,0]
	v_pk_mul_f32 v[54:55], v[54:55], v[72:73] op_sel_hi:[1,0]
	v_add_u32_e32 v68, 0x80, v2
	v_mov_b32_e32 v69, v3
	v_lshlrev_b64 v[68:69], 14, v[68:69]
	v_lshl_add_u64 v[68:69], s[50:51], 0, v[68:69]
	v_lshl_add_u64 v[68:69], v[68:69], 0, v[148:149]
	v_pk_mul_f32 v[54:55], v[134:135], v[54:55]
	v_pk_mul_f32 v[52:53], v[132:133], v[52:53]
	global_store_dwordx4 v[68:69], v[52:55], off offset:528
	v_pk_mul_f32 v[80:81], v[80:81], v[86:87] op_sel_hi:[1,0]
	v_pk_mul_f32 v[82:83], v[82:83], v[86:87] op_sel_hi:[1,0]
	v_add_u32_e32 v52, 0x90, v2
	v_mov_b32_e32 v53, v3
	v_mov_b32_e32 v54, v73
	v_lshlrev_b64 v[52:53], 14, v[52:53]
	v_lshl_add_u64 v[52:53], s[50:51], 0, v[52:53]
	v_pk_mul_f32 v[40:41], v[40:41], v[54:55] op_sel_hi:[1,0]
	v_pk_mul_f32 v[42:43], v[42:43], v[54:55] op_sel_hi:[1,0]
	v_lshl_add_u64 v[52:53], v[52:53], 0, v[148:149]
	v_pk_mul_f32 v[42:43], v[138:139], v[42:43]
	v_pk_mul_f32 v[40:41], v[136:137], v[40:41]
	global_store_dwordx4 v[52:53], v[40:43], off offset:512
	ds_read2_b32 v[40:41], v1 offset0:160 offset1:176
	v_pk_mul_f32 v[36:37], v[36:37], v[54:55] op_sel_hi:[1,0]
	v_pk_mul_f32 v[38:39], v[38:39], v[54:55] op_sel_hi:[1,0]
	v_pk_mul_f32 v[36:37], v[132:133], v[36:37]
	v_pk_mul_f32 v[38:39], v[134:135], v[38:39]
	global_store_dwordx4 v[52:53], v[36:39], off offset:528
	s_waitcnt lgkmcnt(0)
	v_pk_mul_f32 v[20:21], v[20:21], v[40:41] op_sel_hi:[1,0]
	v_pk_mul_f32 v[22:23], v[22:23], v[40:41] op_sel_hi:[1,0]
	v_add_u32_e32 v36, 0xa0, v2
	v_mov_b32_e32 v37, v3
	v_lshlrev_b64 v[36:37], 14, v[36:37]
	v_lshl_add_u64 v[36:37], s[50:51], 0, v[36:37]
	v_lshl_add_u64 v[36:37], v[36:37], 0, v[148:149]
	v_pk_mul_f32 v[22:23], v[134:135], v[22:23]
	v_pk_mul_f32 v[20:21], v[132:133], v[20:21]
	v_add_u32_e32 v2, 0xb0, v2
	global_store_dwordx4 v[36:37], v[20:23], off offset:528
	v_pk_mul_f32 v[76:77], v[76:77], v[86:87] op_sel_hi:[1,0]
	v_pk_mul_f32 v[78:79], v[78:79], v[86:87] op_sel_hi:[1,0]
	v_mov_b32_e32 v20, v41
	v_lshlrev_b64 v[22:23], 14, v[2:3]
	v_pk_mul_f32 v[64:65], v[64:65], v[72:73] op_sel_hi:[1,0]
	v_pk_mul_f32 v[66:67], v[66:67], v[72:73] op_sel_hi:[1,0]
	v_pk_mul_f32 v[60:61], v[60:61], v[72:73] op_sel_hi:[1,0]
	v_pk_mul_f32 v[62:63], v[62:63], v[72:73] op_sel_hi:[1,0]
	v_pk_mul_f32 v[56:57], v[56:57], v[72:73] op_sel_hi:[1,0]
	v_pk_mul_f32 v[58:59], v[58:59], v[72:73] op_sel_hi:[1,0]
	v_pk_mul_f32 v[48:49], v[48:49], v[54:55] op_sel_hi:[1,0]
	v_pk_mul_f32 v[50:51], v[50:51], v[54:55] op_sel_hi:[1,0]
	v_pk_mul_f32 v[44:45], v[44:45], v[54:55] op_sel_hi:[1,0]
	v_pk_mul_f32 v[46:47], v[46:47], v[54:55] op_sel_hi:[1,0]
	v_pk_mul_f32 v[32:33], v[32:33], v[40:41] op_sel_hi:[1,0]
	v_pk_mul_f32 v[34:35], v[34:35], v[40:41] op_sel_hi:[1,0]
	v_pk_mul_f32 v[28:29], v[28:29], v[40:41] op_sel_hi:[1,0]
	v_pk_mul_f32 v[30:31], v[30:31], v[40:41] op_sel_hi:[1,0]
	v_pk_mul_f32 v[24:25], v[24:25], v[40:41] op_sel_hi:[1,0]
	v_pk_mul_f32 v[26:27], v[26:27], v[40:41] op_sel_hi:[1,0]
	v_pk_mul_f32 v[16:17], v[16:17], v[20:21] op_sel_hi:[1,0]
	v_pk_mul_f32 v[18:19], v[18:19], v[20:21] op_sel_hi:[1,0]
	v_lshl_add_u64 v[22:23], s[50:51], 0, v[22:23]
	v_pk_mul_f32 v[12:13], v[12:13], v[20:21] op_sel_hi:[1,0]
	v_pk_mul_f32 v[14:15], v[14:15], v[20:21] op_sel_hi:[1,0]
	v_pk_mul_f32 v[8:9], v[8:9], v[20:21] op_sel_hi:[1,0]
	v_pk_mul_f32 v[10:11], v[10:11], v[20:21] op_sel_hi:[1,0]
	v_pk_mul_f32 v[4:5], v[4:5], v[20:21] op_sel_hi:[1,0]
	v_pk_mul_f32 v[6:7], v[6:7], v[20:21] op_sel_hi:[1,0]
	v_pk_mul_f32 v[82:83], v[146:147], v[82:83]
	v_pk_mul_f32 v[80:81], v[144:145], v[80:81]
	v_pk_mul_f32 v[78:79], v[142:143], v[78:79]
	v_pk_mul_f32 v[76:77], v[140:141], v[76:77]
	v_pk_mul_f32 v[66:67], v[146:147], v[66:67]
	v_pk_mul_f32 v[64:65], v[144:145], v[64:65]
	v_pk_mul_f32 v[62:63], v[142:143], v[62:63]
	v_pk_mul_f32 v[60:61], v[140:141], v[60:61]
	v_pk_mul_f32 v[58:59], v[138:139], v[58:59]
	v_pk_mul_f32 v[56:57], v[136:137], v[56:57]
	v_pk_mul_f32 v[50:51], v[146:147], v[50:51]
	v_pk_mul_f32 v[48:49], v[144:145], v[48:49]
	v_pk_mul_f32 v[46:47], v[142:143], v[46:47]
	v_pk_mul_f32 v[44:45], v[140:141], v[44:45]
	v_pk_mul_f32 v[34:35], v[146:147], v[34:35]
	v_pk_mul_f32 v[32:33], v[144:145], v[32:33]
	v_pk_mul_f32 v[30:31], v[142:143], v[30:31]
	v_pk_mul_f32 v[28:29], v[140:141], v[28:29]
	v_pk_mul_f32 v[26:27], v[138:139], v[26:27]
	v_pk_mul_f32 v[24:25], v[136:137], v[24:25]
	v_pk_mul_f32 v[18:19], v[146:147], v[18:19]
	v_pk_mul_f32 v[16:17], v[144:145], v[16:17]
	v_lshl_add_u64 v[22:23], v[22:23], 0, v[148:149]
	v_pk_mul_f32 v[14:15], v[142:143], v[14:15]
	v_pk_mul_f32 v[12:13], v[140:141], v[12:13]
	v_pk_mul_f32 v[10:11], v[138:139], v[10:11]
	v_pk_mul_f32 v[8:9], v[136:137], v[8:9]
	v_pk_mul_f32 v[6:7], v[134:135], v[6:7]
	v_pk_mul_f32 v[4:5], v[132:133], v[4:5]
	global_store_dwordx4 v[84:85], v[80:83], off
	global_store_dwordx4 v[84:85], v[76:79], off offset:16
	global_store_dwordx4 v[68:69], v[64:67], off
	global_store_dwordx4 v[68:69], v[60:63], off offset:16
	global_store_dwordx4 v[68:69], v[56:59], off offset:512
	global_store_dwordx4 v[52:53], v[48:51], off
	global_store_dwordx4 v[52:53], v[44:47], off offset:16
	global_store_dwordx4 v[36:37], v[32:35], off
	global_store_dwordx4 v[36:37], v[28:31], off offset:16
	global_store_dwordx4 v[36:37], v[24:27], off offset:512
	global_store_dwordx4 v[22:23], v[16:19], off
	global_store_dwordx4 v[22:23], v[12:15], off offset:16
	global_store_dwordx4 v[22:23], v[8:11], off offset:512
	global_store_dwordx4 v[22:23], v[4:7], off offset:528
	s_barrier
	global_load_lds_dwordx4 v[190:191], off
	s_add_i32 m0, s58, 0x12000
	s_nop 0
	global_load_lds_dwordx4 v[188:189], off
	s_add_i32 m0, s58, 0x14000
	s_nop 0
	global_load_lds_dwordx4 v[198:199], off
	s_add_i32 m0, s58, 0x16000
	s_add_u32 s16, s24, s16
	s_addc_u32 s17, s25, 0
	s_add_i32 s60, s58, 0x2000
	global_load_lds_dwordx4 v[196:197], off
	v_lshl_add_u64 v[4:5], s[16:17], 0, v[172:173]
	s_mov_b32 m0, s58
	s_add_u32 s22, s16, 0x2b0000
	global_load_lds_dwordx4 v[4:5], off
	v_lshl_add_u64 v[0:1], s[16:17], 0, v[176:177]
	s_mov_b32 m0, s60
	s_addc_u32 s23, s17, 0
	s_add_i32 s61, s58, 0x4000
	global_load_lds_dwordx4 v[0:1], off
	v_lshl_add_u64 v[6:7], s[22:23], 0, v[172:173]
	s_mov_b32 m0, s61
	s_add_i32 s62, s58, 0x6000
	global_load_lds_dwordx4 v[6:7], off
	v_lshl_add_u64 v[6:7], s[22:23], 0, v[176:177]
	s_mov_b32 m0, s62
	s_cmp_lg_u32 s18, 1
	global_load_lds_dwordx4 v[6:7], off
	s_cbranch_scc1 .LBB0_1017
	s_barrier
	s_setprio 1
